# attention item epilogue: vmcnt(0) for the 16 gain loads moved from right after issue (ahead of a barrier) to their first consumer ~300 instructions later
# speedup vs baseline: 1.0003x; 1.0003x over previous
.LBB0_241:
	s_or_b64 exec, exec, s[8:9]
	v_and_b32_e32 v147, 64, v210
	v_xor_b32_e32 v132, 32, v210
	v_add_u32_e32 v147, 64, v147
	v_cmp_lt_i32_e32 vcc, v132, v147
	s_waitcnt lgkmcnt(0)
	s_barrier
	v_cndmask_b32_e32 v132, v210, v132, vcc
	v_lshlrev_b32_e32 v147, 2, v132
	ds_bpermute_b32 v132, v147, v160
	s_waitcnt lgkmcnt(0)
	v_add_f32_e32 v132, v160, v132
	s_and_saveexec_b64 s[8:9], s[60:61]
	s_cbranch_execz .LBB0_243
	v_div_scale_f32 v151, s[6:7], v132, v132, v134
	v_rcp_f32_e32 v153, v151
	v_div_scale_f32 v155, vcc, v134, v132, v134
	v_fma_f32 v157, -v151, v153, 1.0
	v_fmac_f32_e32 v153, v157, v153
	v_mul_f32_e32 v157, v155, v153
	v_fma_f32 v160, -v151, v157, v155
	v_fmac_f32_e32 v157, v160, v153
	v_fma_f32 v151, -v151, v157, v155
	v_div_fmas_f32 v151, v151, v153, v157
	v_div_fixup_f32 v151, v151, v132, v134
	v_mul_f32_e32 v153, v50, v151
	v_mul_f32_e32 v155, v51, v151
	ds_write2st64_b32 v199, v153, v155 offset1:1
	v_mul_f32_e32 v153, v52, v151
	v_mul_f32_e32 v155, v53, v151
	ds_write2st64_b32 v199, v153, v155 offset0:2 offset1:3
	v_mul_f32_e32 v153, v54, v151
	v_mul_f32_e32 v155, v55, v151
	ds_write2st64_b32 v199, v153, v155 offset0:4 offset1:5
	v_mul_f32_e32 v153, v56, v151
	v_mul_f32_e32 v155, v57, v151
	ds_write2st64_b32 v199, v153, v155 offset0:6 offset1:7
	v_mul_f32_e32 v153, v58, v151
	v_mul_f32_e32 v155, v59, v151
	ds_write2st64_b32 v199, v153, v155 offset0:8 offset1:9
	v_mul_f32_e32 v153, v60, v151
	v_mul_f32_e32 v155, v61, v151
	ds_write2st64_b32 v199, v153, v155 offset0:10 offset1:11
	v_mul_f32_e32 v153, v62, v151
	v_mul_f32_e32 v155, v63, v151
	ds_write2st64_b32 v199, v153, v155 offset0:12 offset1:13
	v_mul_f32_e32 v153, v64, v151
	v_mul_f32_e32 v155, v65, v151
	ds_write2st64_b32 v199, v153, v155 offset0:14 offset1:15
	v_mul_f32_e32 v153, v34, v151
	v_mul_f32_e32 v155, v35, v151
	ds_write2st64_b32 v199, v153, v155 offset0:16 offset1:17
	v_mul_f32_e32 v153, v36, v151
	v_mul_f32_e32 v155, v37, v151
	ds_write2st64_b32 v199, v153, v155 offset0:18 offset1:19
	v_mul_f32_e32 v153, v38, v151
	v_mul_f32_e32 v155, v39, v151
	ds_write2st64_b32 v199, v153, v155 offset0:20 offset1:21
	v_mul_f32_e32 v153, v40, v151
	v_mul_f32_e32 v155, v41, v151
	ds_write2st64_b32 v199, v153, v155 offset0:22 offset1:23
	v_mul_f32_e32 v153, v42, v151
	v_mul_f32_e32 v155, v43, v151
	ds_write2st64_b32 v199, v153, v155 offset0:24 offset1:25
	v_mul_f32_e32 v153, v44, v151
	v_mul_f32_e32 v155, v45, v151
	ds_write2st64_b32 v199, v153, v155 offset0:26 offset1:27
	v_mul_f32_e32 v153, v46, v151
	v_mul_f32_e32 v155, v47, v151
	ds_write2st64_b32 v199, v153, v155 offset0:28 offset1:29
	v_mul_f32_e32 v153, v48, v151
	v_mul_f32_e32 v155, v49, v151
	ds_write2st64_b32 v199, v153, v155 offset0:30 offset1:31
	v_mul_f32_e32 v153, v18, v151
	v_mul_f32_e32 v155, v19, v151
	ds_write2st64_b32 v199, v153, v155 offset0:32 offset1:33
	v_mul_f32_e32 v153, v20, v151
	v_mul_f32_e32 v155, v21, v151
	ds_write2st64_b32 v199, v153, v155 offset0:34 offset1:35
	v_mul_f32_e32 v153, v22, v151
	v_mul_f32_e32 v155, v23, v151
	ds_write2st64_b32 v199, v153, v155 offset0:36 offset1:37
	v_mul_f32_e32 v153, v24, v151
	v_mul_f32_e32 v155, v25, v151
	ds_write2st64_b32 v199, v153, v155 offset0:38 offset1:39
	v_mul_f32_e32 v153, v26, v151
	v_mul_f32_e32 v155, v27, v151
	ds_write2st64_b32 v199, v153, v155 offset0:40 offset1:41
	v_mul_f32_e32 v153, v28, v151
	v_mul_f32_e32 v155, v29, v151
	ds_write2st64_b32 v199, v153, v155 offset0:42 offset1:43
	v_mul_f32_e32 v153, v30, v151
	v_mul_f32_e32 v155, v31, v151
	ds_write2st64_b32 v199, v153, v155 offset0:44 offset1:45
	v_mul_f32_e32 v153, v32, v151
	v_mul_f32_e32 v155, v33, v151
	ds_write2st64_b32 v199, v153, v155 offset0:46 offset1:47
	v_mul_f32_e32 v153, v2, v151
	v_mul_f32_e32 v155, v3, v151
	ds_write2st64_b32 v199, v153, v155 offset0:48 offset1:49
	v_mul_f32_e32 v153, v4, v151
	v_mul_f32_e32 v155, v5, v151
	ds_write2st64_b32 v199, v153, v155 offset0:50 offset1:51
	v_mul_f32_e32 v153, v6, v151
	v_mul_f32_e32 v155, v7, v151
	ds_write2st64_b32 v199, v153, v155 offset0:52 offset1:53
	v_mul_f32_e32 v153, v8, v151
	v_mul_f32_e32 v155, v9, v151
	ds_write2st64_b32 v199, v153, v155 offset0:54 offset1:55
	v_mul_f32_e32 v153, v10, v151
	v_mul_f32_e32 v155, v11, v151
	ds_write2st64_b32 v199, v153, v155 offset0:56 offset1:57
	v_mul_f32_e32 v153, v12, v151
	v_mul_f32_e32 v155, v13, v151
	ds_write2st64_b32 v199, v153, v155 offset0:58 offset1:59
	v_mul_f32_e32 v153, v14, v151
	v_mul_f32_e32 v155, v15, v151
	ds_write2st64_b32 v199, v153, v155 offset0:60 offset1:61
	v_mul_f32_e32 v153, v16, v151
	v_mul_f32_e32 v151, v17, v151
	ds_write2st64_b32 v199, v153, v151 offset0:62 offset1:63
.LBB0_243:
	s_or_b64 exec, exec, s[8:9]
	s_waitcnt lgkmcnt(0)
	s_barrier
	s_and_saveexec_b64 s[8:9], s[52:53]
	s_cbranch_execz .LBB0_214
	v_rcp_f32_e32 v132, v132
	ds_read2st64_b32 v[160:161], v199 offset1:1
	ds_read2st64_b32 v[162:163], v199 offset0:2 offset1:3
	ds_read2st64_b32 v[164:165], v199 offset0:4 offset1:5
	ds_read2st64_b32 v[166:167], v199 offset0:6 offset1:7
	ds_read2st64_b32 v[168:169], v199 offset0:8 offset1:9
	ds_read2st64_b32 v[170:171], v199 offset0:10 offset1:11
	ds_read2st64_b32 v[172:173], v199 offset0:12 offset1:13
	ds_read2st64_b32 v[174:175], v199 offset0:14 offset1:15
	ds_read2st64_b32 v[176:177], v199 offset0:16 offset1:17
	ds_read2st64_b32 v[178:179], v199 offset0:18 offset1:19
	ds_read2st64_b32 v[180:181], v199 offset0:20 offset1:21
	ds_read2st64_b32 v[182:183], v199 offset0:22 offset1:23
	ds_read2st64_b32 v[184:185], v199 offset0:24 offset1:25
	ds_read2st64_b32 v[186:187], v199 offset0:26 offset1:27
	ds_read2st64_b32 v[188:189], v199 offset0:28 offset1:29
	ds_read2st64_b32 v[212:213], v199 offset0:30 offset1:31
	ds_read2st64_b32 v[214:215], v199 offset0:32 offset1:33
	ds_read2st64_b32 v[216:217], v199 offset0:34 offset1:35
	ds_read2st64_b32 v[218:219], v199 offset0:36 offset1:37
	ds_read2st64_b32 v[220:221], v199 offset0:38 offset1:39
	ds_read2st64_b32 v[222:223], v199 offset0:40 offset1:41
	ds_read2st64_b32 v[224:225], v199 offset0:42 offset1:43
	ds_read2st64_b32 v[226:227], v199 offset0:44 offset1:45
	ds_read2st64_b32 v[228:229], v199 offset0:46 offset1:47
	ds_read2st64_b32 v[230:231], v199 offset0:56 offset1:57
	ds_read2st64_b32 v[232:233], v199 offset0:58 offset1:59
	ds_read2st64_b32 v[234:235], v199 offset0:60 offset1:61
	ds_read2st64_b32 v[236:237], v199 offset0:62 offset1:63
	ds_read2st64_b32 v[238:239], v199 offset0:48 offset1:49
	ds_read2st64_b32 v[240:241], v199 offset0:50 offset1:51
	ds_read2st64_b32 v[242:243], v199 offset0:52 offset1:53
	ds_read2st64_b32 v[244:245], v199 offset0:54 offset1:55
	v_mov_b32_e32 v153, v133
	s_waitcnt lgkmcnt(14)
	v_pk_fma_f32 v[50:51], v[50:51], v[132:133], v[160:161] op_sel_hi:[1,0,1] neg_lo:[0,0,1] neg_hi:[0,0,1]
	v_pk_fma_f32 v[52:53], v[52:53], v[132:133], v[162:163] op_sel_hi:[1,0,1] neg_lo:[0,0,1] neg_hi:[0,0,1]
	v_pk_mul_f32 v[160:161], v[50:51], v[50:51]
	s_waitcnt lgkmcnt(5)
	v_pk_fma_f32 v[14:15], v[14:15], v[132:133], v[234:235] op_sel_hi:[1,0,1] neg_lo:[0,0,1] neg_hi:[0,0,1]
	s_waitcnt lgkmcnt(4)
	v_pk_fma_f32 v[16:17], v[16:17], v[132:133], v[236:237] op_sel_hi:[1,0,1] neg_lo:[0,0,1] neg_hi:[0,0,1]
	v_pk_mul_f32 v[162:163], v[52:53], v[52:53]
	v_pk_fma_f32 v[56:57], v[56:57], v[132:133], v[166:167] op_sel_hi:[1,0,1] neg_lo:[0,0,1] neg_hi:[0,0,1]
	v_pk_fma_f32 v[54:55], v[54:55], v[132:133], v[164:165] op_sel_hi:[1,0,1] neg_lo:[0,0,1] neg_hi:[0,0,1]
	v_pk_fma_f32 v[60:61], v[60:61], v[132:133], v[170:171] op_sel_hi:[1,0,1] neg_lo:[0,0,1] neg_hi:[0,0,1]
	v_pk_fma_f32 v[58:59], v[58:59], v[132:133], v[168:169] op_sel_hi:[1,0,1] neg_lo:[0,0,1] neg_hi:[0,0,1]
	v_pk_fma_f32 v[64:65], v[64:65], v[132:133], v[174:175] op_sel_hi:[1,0,1] neg_lo:[0,0,1] neg_hi:[0,0,1]
	v_pk_fma_f32 v[62:63], v[62:63], v[132:133], v[172:173] op_sel_hi:[1,0,1] neg_lo:[0,0,1] neg_hi:[0,0,1]
	v_pk_fma_f32 v[36:37], v[36:37], v[132:133], v[178:179] op_sel_hi:[1,0,1] neg_lo:[0,0,1] neg_hi:[0,0,1]
	v_pk_fma_f32 v[34:35], v[34:35], v[132:133], v[176:177] op_sel_hi:[1,0,1] neg_lo:[0,0,1] neg_hi:[0,0,1]
	v_pk_fma_f32 v[40:41], v[40:41], v[132:133], v[182:183] op_sel_hi:[1,0,1] neg_lo:[0,0,1] neg_hi:[0,0,1]
	v_pk_fma_f32 v[38:39], v[38:39], v[132:133], v[180:181] op_sel_hi:[1,0,1] neg_lo:[0,0,1] neg_hi:[0,0,1]
	v_pk_fma_f32 v[44:45], v[44:45], v[132:133], v[186:187] op_sel_hi:[1,0,1] neg_lo:[0,0,1] neg_hi:[0,0,1]
	v_pk_fma_f32 v[42:43], v[42:43], v[132:133], v[184:185] op_sel_hi:[1,0,1] neg_lo:[0,0,1] neg_hi:[0,0,1]
	v_pk_fma_f32 v[48:49], v[48:49], v[132:133], v[212:213] op_sel_hi:[1,0,1] neg_lo:[0,0,1] neg_hi:[0,0,1]
	v_pk_fma_f32 v[46:47], v[46:47], v[132:133], v[188:189] op_sel_hi:[1,0,1] neg_lo:[0,0,1] neg_hi:[0,0,1]
	v_pk_fma_f32 v[20:21], v[20:21], v[132:133], v[216:217] op_sel_hi:[1,0,1] neg_lo:[0,0,1] neg_hi:[0,0,1]
	v_pk_fma_f32 v[18:19], v[18:19], v[132:133], v[214:215] op_sel_hi:[1,0,1] neg_lo:[0,0,1] neg_hi:[0,0,1]
	v_pk_fma_f32 v[24:25], v[24:25], v[132:133], v[220:221] op_sel_hi:[1,0,1] neg_lo:[0,0,1] neg_hi:[0,0,1]
	v_pk_fma_f32 v[22:23], v[22:23], v[132:133], v[218:219] op_sel_hi:[1,0,1] neg_lo:[0,0,1] neg_hi:[0,0,1]
	v_pk_fma_f32 v[28:29], v[28:29], v[132:133], v[224:225] op_sel_hi:[1,0,1] neg_lo:[0,0,1] neg_hi:[0,0,1]
	v_pk_fma_f32 v[26:27], v[26:27], v[132:133], v[222:223] op_sel_hi:[1,0,1] neg_lo:[0,0,1] neg_hi:[0,0,1]
	v_pk_fma_f32 v[32:33], v[32:33], v[132:133], v[228:229] op_sel_hi:[1,0,1] neg_lo:[0,0,1] neg_hi:[0,0,1]
	v_pk_fma_f32 v[30:31], v[30:31], v[132:133], v[226:227] op_sel_hi:[1,0,1] neg_lo:[0,0,1] neg_hi:[0,0,1]
	s_waitcnt lgkmcnt(2)
	v_pk_fma_f32 v[4:5], v[4:5], v[132:133], v[240:241] op_sel_hi:[1,0,1] neg_lo:[0,0,1] neg_hi:[0,0,1]
	v_pk_fma_f32 v[2:3], v[2:3], v[132:133], v[238:239] op_sel_hi:[1,0,1] neg_lo:[0,0,1] neg_hi:[0,0,1]
	s_waitcnt lgkmcnt(0)
	v_pk_fma_f32 v[8:9], v[8:9], v[132:133], v[244:245] op_sel_hi:[1,0,1] neg_lo:[0,0,1] neg_hi:[0,0,1]
	v_pk_fma_f32 v[6:7], v[6:7], v[132:133], v[242:243] op_sel_hi:[1,0,1] neg_lo:[0,0,1] neg_hi:[0,0,1]
	v_pk_fma_f32 v[12:13], v[12:13], v[132:133], v[232:233] op_sel_hi:[1,0,1] neg_lo:[0,0,1] neg_hi:[0,0,1]
	v_pk_fma_f32 v[10:11], v[10:11], v[132:133], v[230:231] op_sel_hi:[1,0,1] neg_lo:[0,0,1] neg_hi:[0,0,1]
	v_add_f32_e32 v132, v160, v161
	v_add_f32_e32 v132, v132, v162
	v_pk_mul_f32 v[164:165], v[54:55], v[54:55]
	v_add_f32_e32 v132, v132, v163
	v_add_f32_e32 v132, v132, v164
	v_pk_mul_f32 v[166:167], v[56:57], v[56:57]
	v_add_f32_e32 v132, v132, v165
	v_add_f32_e32 v132, v132, v166
	v_pk_mul_f32 v[168:169], v[58:59], v[58:59]
	v_add_f32_e32 v132, v132, v167
	v_add_f32_e32 v132, v132, v168
	v_pk_mul_f32 v[170:171], v[60:61], v[60:61]
	v_add_f32_e32 v132, v132, v169
	v_add_f32_e32 v132, v132, v170
	v_pk_mul_f32 v[172:173], v[62:63], v[62:63]
	v_add_f32_e32 v132, v132, v171
	v_add_f32_e32 v132, v132, v172
	v_pk_mul_f32 v[174:175], v[64:65], v[64:65]
	v_add_f32_e32 v132, v132, v173
	v_add_f32_e32 v132, v132, v174
	v_pk_mul_f32 v[176:177], v[34:35], v[34:35]
	v_add_f32_e32 v132, v132, v175
	v_add_f32_e32 v132, v132, v176
	v_pk_mul_f32 v[178:179], v[36:37], v[36:37]
	v_add_f32_e32 v132, v132, v177
	v_add_f32_e32 v132, v132, v178
	v_pk_mul_f32 v[180:181], v[38:39], v[38:39]
	v_add_f32_e32 v132, v132, v179
	v_add_f32_e32 v132, v132, v180
	v_pk_mul_f32 v[182:183], v[40:41], v[40:41]
	v_add_f32_e32 v132, v132, v181
	v_add_f32_e32 v132, v132, v182
	v_pk_mul_f32 v[184:185], v[42:43], v[42:43]
	v_add_f32_e32 v132, v132, v183
	v_add_f32_e32 v132, v132, v184
	v_pk_mul_f32 v[186:187], v[44:45], v[44:45]
	v_add_f32_e32 v132, v132, v185
	v_add_f32_e32 v132, v132, v186
	v_pk_mul_f32 v[188:189], v[46:47], v[46:47]
	v_add_f32_e32 v132, v132, v187
	v_add_f32_e32 v132, v132, v188
	v_pk_mul_f32 v[212:213], v[48:49], v[48:49]
	v_add_f32_e32 v132, v132, v189
	v_add_f32_e32 v132, v132, v212
	v_pk_mul_f32 v[214:215], v[18:19], v[18:19]
	v_add_f32_e32 v132, v132, v213
	v_add_f32_e32 v132, v132, v214
	v_pk_mul_f32 v[216:217], v[20:21], v[20:21]
	v_add_f32_e32 v132, v132, v215
	v_add_f32_e32 v132, v132, v216
	v_pk_mul_f32 v[218:219], v[22:23], v[22:23]
	v_add_f32_e32 v132, v132, v217
	v_add_f32_e32 v132, v132, v218
	v_pk_mul_f32 v[220:221], v[24:25], v[24:25]
	v_add_f32_e32 v132, v132, v219
	v_add_f32_e32 v132, v132, v220
	v_pk_mul_f32 v[222:223], v[26:27], v[26:27]
	v_add_f32_e32 v132, v132, v221
	v_add_f32_e32 v132, v132, v222
	v_pk_mul_f32 v[224:225], v[28:29], v[28:29]
	v_add_f32_e32 v132, v132, v223
	v_add_f32_e32 v132, v132, v224
	v_pk_mul_f32 v[226:227], v[30:31], v[30:31]
	v_add_f32_e32 v132, v132, v225
	v_add_f32_e32 v132, v132, v226
	v_pk_mul_f32 v[228:229], v[32:33], v[32:33]
	v_add_f32_e32 v132, v132, v227
	v_add_f32_e32 v132, v132, v228
	v_pk_mul_f32 v[238:239], v[2:3], v[2:3]
	v_add_f32_e32 v132, v132, v229
	v_add_f32_e32 v132, v132, v238
	v_pk_mul_f32 v[240:241], v[4:5], v[4:5]
	v_add_f32_e32 v132, v132, v239
	v_add_f32_e32 v132, v132, v240
	v_pk_mul_f32 v[242:243], v[6:7], v[6:7]
	v_add_f32_e32 v132, v132, v241
	v_add_f32_e32 v132, v132, v242
	v_pk_mul_f32 v[244:245], v[8:9], v[8:9]
	v_add_f32_e32 v132, v132, v243
	v_add_f32_e32 v132, v132, v244
	v_pk_mul_f32 v[230:231], v[10:11], v[10:11]
	v_add_f32_e32 v132, v132, v245
	v_add_f32_e32 v132, v132, v230
	v_pk_mul_f32 v[232:233], v[12:13], v[12:13]
	v_add_f32_e32 v132, v132, v231
	v_add_f32_e32 v132, v132, v232
	v_pk_mul_f32 v[234:235], v[14:15], v[14:15]
	v_add_f32_e32 v132, v132, v233
	v_add_f32_e32 v132, v132, v234
	v_pk_mul_f32 v[236:237], v[16:17], v[16:17]
	v_add_f32_e32 v132, v132, v235
	v_add_f32_e32 v132, v132, v236
	v_add_f32_e32 v151, v132, v237
	ds_bpermute_b32 v147, v147, v151
	v_lshlrev_b32_e32 v132, 1, v141
	v_lshl_add_u64 v[160:161], s[80:81], 0, v[132:133]
	v_lshl_add_u64 v[158:159], v[158:159], 1, v[160:161]
	v_lshl_add_u64 v[158:159], v[158:159], 0, v[152:153]
	s_waitcnt lgkmcnt(0)
	v_add_f32_e32 v132, v151, v147
	v_fmamk_f32 v132, v132, 0x3c000000, v135
	v_mul_f32_e32 v141, 0x4b800000, v132
	v_cmp_gt_f32_e32 vcc, s11, v132
	s_nop 1
	v_cndmask_b32_e32 v132, v132, v141, vcc
	v_rsq_f32_e32 v132, v132
	s_nop 0
	v_mul_f32_e32 v141, 0x45800000, v132
	v_cndmask_b32_e32 v132, v132, v141, vcc
	v_mul_f32_e32 v132, 0x3f4ccccd, v132
	v_pk_mul_f32 v[50:51], v[50:51], v[132:133] op_sel_hi:[1,0]
	v_pk_mul_f32 v[52:53], v[52:53], v[132:133] op_sel_hi:[1,0]
	v_pk_mul_f32 v[34:35], v[34:35], v[132:133] op_sel_hi:[1,0]
	v_pk_mul_f32 v[36:37], v[36:37], v[132:133] op_sel_hi:[1,0]
	v_pk_mul_f32 v[18:19], v[18:19], v[132:133] op_sel_hi:[1,0]
	v_pk_mul_f32 v[20:21], v[20:21], v[132:133] op_sel_hi:[1,0]
	v_pk_mul_f32 v[2:3], v[2:3], v[132:133] op_sel_hi:[1,0]
	v_pk_mul_f32 v[4:5], v[4:5], v[132:133] op_sel_hi:[1,0]
	s_waitcnt vmcnt(0)
	v_pk_mul_f32 v[50:51], v[66:67], v[50:51]
	v_pk_mul_f32 v[52:53], v[68:69], v[52:53]
	v_pk_mul_f32 v[34:35], v[82:83], v[34:35]
	v_pk_mul_f32 v[36:37], v[84:85], v[36:37]
	v_pk_mul_f32 v[18:19], v[98:99], v[18:19]
	v_pk_mul_f32 v[20:21], v[100:101], v[20:21]
	v_pk_mul_f32 v[2:3], v[114:115], v[2:3]
	v_pk_mul_f32 v[4:5], v[116:117], v[4:5]
	v_mbcnt_lo_u32_b32 v230, -1, 0
	v_mbcnt_hi_u32_b32 v230, -1, v230
	v_and_b32_e32 v230, 32, v230
	v_lshrrev_b32_e32 v230, 2, v230
	v_mov_b32_e32 v231, 0
	v_cvt_pk_bf16_f32 v212, v50, v51
	v_cvt_pk_bf16_f32 v213, v52, v53
	v_cvt_pk_bf16_f32 v216, v34, v35
	v_cvt_pk_bf16_f32 v217, v36, v37
	v_cvt_pk_bf16_f32 v220, v18, v19
	v_cvt_pk_bf16_f32 v221, v20, v21
	v_cvt_pk_bf16_f32 v224, v2, v3
	v_cvt_pk_bf16_f32 v225, v4, v5
	v_pk_mul_f32 v[50:51], v[54:55], v[132:133] op_sel_hi:[1,0]
	v_pk_mul_f32 v[52:53], v[56:57], v[132:133] op_sel_hi:[1,0]
	v_pk_mul_f32 v[34:35], v[38:39], v[132:133] op_sel_hi:[1,0]
	v_pk_mul_f32 v[36:37], v[40:41], v[132:133] op_sel_hi:[1,0]
	v_pk_mul_f32 v[18:19], v[22:23], v[132:133] op_sel_hi:[1,0]
	v_pk_mul_f32 v[20:21], v[24:25], v[132:133] op_sel_hi:[1,0]
	v_pk_mul_f32 v[2:3], v[6:7], v[132:133] op_sel_hi:[1,0]
	v_pk_mul_f32 v[4:5], v[8:9], v[132:133] op_sel_hi:[1,0]
	v_pk_mul_f32 v[50:51], v[70:71], v[50:51]
	v_pk_mul_f32 v[52:53], v[72:73], v[52:53]
	v_pk_mul_f32 v[34:35], v[86:87], v[34:35]
	v_pk_mul_f32 v[36:37], v[88:89], v[36:37]
	v_pk_mul_f32 v[18:19], v[102:103], v[18:19]
	v_pk_mul_f32 v[20:21], v[104:105], v[20:21]
	v_pk_mul_f32 v[2:3], v[118:119], v[2:3]
	v_pk_mul_f32 v[4:5], v[120:121], v[4:5]
	v_cvt_pk_bf16_f32 v214, v50, v51
	v_cvt_pk_bf16_f32 v215, v52, v53
	v_cvt_pk_bf16_f32 v218, v34, v35
	v_cvt_pk_bf16_f32 v219, v36, v37
	v_cvt_pk_bf16_f32 v222, v18, v19
	v_cvt_pk_bf16_f32 v223, v20, v21
	v_cvt_pk_bf16_f32 v226, v2, v3
	v_cvt_pk_bf16_f32 v227, v4, v5
	v_pk_mul_f32 v[50:51], v[58:59], v[132:133] op_sel_hi:[1,0]
	v_pk_mul_f32 v[52:53], v[60:61], v[132:133] op_sel_hi:[1,0]
	v_pk_mul_f32 v[34:35], v[42:43], v[132:133] op_sel_hi:[1,0]
	v_pk_mul_f32 v[36:37], v[44:45], v[132:133] op_sel_hi:[1,0]
	v_pk_mul_f32 v[18:19], v[26:27], v[132:133] op_sel_hi:[1,0]
	v_pk_mul_f32 v[20:21], v[28:29], v[132:133] op_sel_hi:[1,0]
	s_nop 1
	v_permlane32_swap_b32_e32 v212, v214
	v_permlane32_swap_b32_e32 v213, v215
	v_permlane32_swap_b32_e32 v216, v218
	v_permlane32_swap_b32_e32 v217, v219
	v_permlane32_swap_b32_e32 v220, v222
	v_permlane32_swap_b32_e32 v221, v223
	v_permlane32_swap_b32_e32 v224, v226
	v_permlane32_swap_b32_e32 v225, v227
	v_lshl_add_u64 v[228:229], v[158:159], 0, v[230:231]
	global_store_dwordx4 v[228:229], v[212:215], off
	global_store_dwordx4 v[228:229], v[216:219], off offset:64
	global_store_dwordx4 v[228:229], v[220:223], off offset:128
	global_store_dwordx4 v[228:229], v[224:227], off offset:192
	v_pk_mul_f32 v[2:3], v[10:11], v[132:133] op_sel_hi:[1,0]
	v_pk_mul_f32 v[4:5], v[12:13], v[132:133] op_sel_hi:[1,0]
	v_pk_mul_f32 v[50:51], v[74:75], v[50:51]
	v_pk_mul_f32 v[52:53], v[76:77], v[52:53]
	v_pk_mul_f32 v[34:35], v[90:91], v[34:35]
	v_pk_mul_f32 v[36:37], v[92:93], v[36:37]
	v_pk_mul_f32 v[18:19], v[106:107], v[18:19]
	v_pk_mul_f32 v[20:21], v[108:109], v[20:21]
	v_pk_mul_f32 v[2:3], v[122:123], v[2:3]
	v_pk_mul_f32 v[4:5], v[124:125], v[4:5]
	v_cvt_pk_bf16_f32 v212, v50, v51
	v_cvt_pk_bf16_f32 v213, v52, v53
	v_cvt_pk_bf16_f32 v216, v34, v35
	v_cvt_pk_bf16_f32 v217, v36, v37
	v_cvt_pk_bf16_f32 v220, v18, v19
	v_cvt_pk_bf16_f32 v221, v20, v21
	v_cvt_pk_bf16_f32 v224, v2, v3
	v_cvt_pk_bf16_f32 v225, v4, v5
	v_pk_mul_f32 v[50:51], v[62:63], v[132:133] op_sel_hi:[1,0]
	v_pk_mul_f32 v[52:53], v[64:65], v[132:133] op_sel_hi:[1,0]
	v_pk_mul_f32 v[34:35], v[46:47], v[132:133] op_sel_hi:[1,0]
	v_pk_mul_f32 v[36:37], v[48:49], v[132:133] op_sel_hi:[1,0]
	v_pk_mul_f32 v[18:19], v[30:31], v[132:133] op_sel_hi:[1,0]
	v_pk_mul_f32 v[20:21], v[32:33], v[132:133] op_sel_hi:[1,0]
	v_pk_mul_f32 v[2:3], v[14:15], v[132:133] op_sel_hi:[1,0]
	v_pk_mul_f32 v[4:5], v[16:17], v[132:133] op_sel_hi:[1,0]
	v_pk_mul_f32 v[50:51], v[78:79], v[50:51]
	v_pk_mul_f32 v[52:53], v[80:81], v[52:53]
	v_pk_mul_f32 v[34:35], v[94:95], v[34:35]
	v_pk_mul_f32 v[36:37], v[96:97], v[36:37]
	v_pk_mul_f32 v[18:19], v[110:111], v[18:19]
	v_pk_mul_f32 v[20:21], v[112:113], v[20:21]
	v_pk_mul_f32 v[2:3], v[126:127], v[2:3]
	v_pk_mul_f32 v[4:5], v[128:129], v[4:5]
	v_cvt_pk_bf16_f32 v214, v50, v51
	v_cvt_pk_bf16_f32 v215, v52, v53
	v_cvt_pk_bf16_f32 v218, v34, v35
	v_cvt_pk_bf16_f32 v219, v36, v37
	v_cvt_pk_bf16_f32 v222, v18, v19
	v_cvt_pk_bf16_f32 v223, v20, v21
	v_cvt_pk_bf16_f32 v226, v2, v3
	v_cvt_pk_bf16_f32 v227, v4, v5
	s_nop 1
	v_permlane32_swap_b32_e32 v212, v214
	v_permlane32_swap_b32_e32 v213, v215
	v_permlane32_swap_b32_e32 v216, v218
	v_permlane32_swap_b32_e32 v217, v219
	v_permlane32_swap_b32_e32 v220, v222
	v_permlane32_swap_b32_e32 v221, v223
	v_permlane32_swap_b32_e32 v224, v226
	v_permlane32_swap_b32_e32 v225, v227
	v_lshl_add_u64 v[228:229], v[158:159], 0, v[230:231]
	global_store_dwordx4 v[228:229], v[212:215], off offset:32
	global_store_dwordx4 v[228:229], v[216:219], off offset:96
	global_store_dwordx4 v[228:229], v[220:223], off offset:160
	global_store_dwordx4 v[228:229], v[224:227], off offset:224
	s_branch .LBB0_214
